# band (mode 0) attention step hand-scheduled like FoX; relative-bias gather replaced by 4 shifted reversed LDS table copies read with ds_read_b128; next-tile bias init before the barrier
# baseline (speedup 1.0000x reference)
; __device__ __forceinline__ int crow(int r, int hi) { return (r & 3) + 8 * (r >> 2) + 4 * hi; }
; template <int MODE>
; __device__ __forceinline__ void step64(St& S, const bf16x8 (&qf)[4], int t, int qpos0, bool diag, bool first, float cq, float cfar, const LAS float* tab,
;                                        const LAS unsigned char* buf, unsigned vaddr, int r32, int hi) {
;     ...
;             const int dd = qpos0 + r32 - t * 64 + 128;
; #pragma unroll
;             for (int r = 0; r < 16; ++r) { int idx = dd - crow(r, hi); idx = idx < 0 ? 0 : (idx > 256 ? 256 : idx); sa[r] = tab[idx] - S.m; }
; __device__ __forceinline__ void phase2(const Params& P, LAS unsigned char* lds, int tid, int lane, int wave) {
;     ...
;             const float* C2P = (const float*)(P.ws + WS_C2P); const float* C2S = (const float*)(P.ws + WS_C2S);
;             for (int i = tid; i < 2048; i += 512) c2p[i] = C2P[(size_t)vb * 2048 + i];
;             if (vb < 64) for (int i = tid; i < LBS_LEN; i += 512) c2s[i] = C2S[(size_t)vb * LBS_LEN + i];
;             for (int i = tid; i < NREL; i += 512) rb2[i] = P.relb[h * NREL + i] * LOG2E;
;         }
;         __syncthreads();
.LBB0_545:
	s_or_b64 exec, exec, s[0:1]
	s_cmpk_lt_i32 s96, 0x80
	s_mov_b64 s[0:1], -1
	s_waitcnt lgkmcnt(0)
	s_barrier
	v_mov_b32_e32 v230, v120
	v_min_u32_e32 v230, 1183, v230
	v_mov_b32_e32 v231, 0
	v_cmp_le_u32_e32 vcc, 296, v230
	s_nop 1
	v_addc_co_u32_e32 v231, vcc, 0, v231, vcc
	v_cmp_le_u32_e32 vcc, 592, v230
	s_nop 1
	v_addc_co_u32_e32 v231, vcc, 0, v231, vcc
	v_cmp_le_u32_e32 vcc, 888, v230
	s_nop 1
	v_addc_co_u32_e32 v231, vcc, 0, v231, vcc
	v_mul_u32_u24_e32 v232, 296, v231
	v_sub_u32_e32 v232, v230, v232
	v_add_u32_e32 v232, v232, v231
	v_sub_u32_e32 v232, 352, v232
	v_max_i32_e32 v232, 0, v232
	v_min_i32_e32 v232, 0x100, v232
	v_lshlrev_b32_e32 v232, 2, v232
	ds_read_b32 v233, v232 offset:16640
	v_lshlrev_b32_e32 v230, 2, v230
	v_add_u32_e32 v230, 137216, v230
	s_waitcnt lgkmcnt(0)
	ds_write_b32 v230, v233
	v_add_u32_e32 v230, 512, v120
	v_min_u32_e32 v230, 1183, v230
	v_mov_b32_e32 v231, 0
	v_cmp_le_u32_e32 vcc, 296, v230
	s_nop 1
	v_addc_co_u32_e32 v231, vcc, 0, v231, vcc
	v_cmp_le_u32_e32 vcc, 592, v230
	s_nop 1
	v_addc_co_u32_e32 v231, vcc, 0, v231, vcc
	v_cmp_le_u32_e32 vcc, 888, v230
	s_nop 1
	v_addc_co_u32_e32 v231, vcc, 0, v231, vcc
	v_mul_u32_u24_e32 v232, 296, v231
	v_sub_u32_e32 v232, v230, v232
	v_add_u32_e32 v232, v232, v231
	v_sub_u32_e32 v232, 352, v232
	v_max_i32_e32 v232, 0, v232
	v_min_i32_e32 v232, 0x100, v232
	v_lshlrev_b32_e32 v232, 2, v232
	ds_read_b32 v233, v232 offset:16640
	v_lshlrev_b32_e32 v230, 2, v230
	v_add_u32_e32 v230, 137216, v230
	s_waitcnt lgkmcnt(0)
	ds_write_b32 v230, v233
	v_add_u32_e32 v230, 1024, v120
	v_min_u32_e32 v230, 1183, v230
	v_mov_b32_e32 v231, 0
	v_cmp_le_u32_e32 vcc, 296, v230
	s_nop 1
	v_addc_co_u32_e32 v231, vcc, 0, v231, vcc
	v_cmp_le_u32_e32 vcc, 592, v230
	s_nop 1
	v_addc_co_u32_e32 v231, vcc, 0, v231, vcc
	v_cmp_le_u32_e32 vcc, 888, v230
	s_nop 1
	v_addc_co_u32_e32 v231, vcc, 0, v231, vcc
	v_mul_u32_u24_e32 v232, 296, v231
	v_sub_u32_e32 v232, v230, v232
	v_add_u32_e32 v232, v232, v231
	v_sub_u32_e32 v232, 352, v232
	v_max_i32_e32 v232, 0, v232
	v_min_i32_e32 v232, 0x100, v232
	v_lshlrev_b32_e32 v232, 2, v232
	ds_read_b32 v233, v232 offset:16640
	v_lshlrev_b32_e32 v230, 2, v230
	v_add_u32_e32 v230, 137216, v230
	s_waitcnt lgkmcnt(0)
	ds_write_b32 v230, v233
	s_cbranch_scc1 .LBB0_547
	s_lshl_b32 s12, s14, 6
	s_mov_b64 s[0:1], 0
	s_mov_b64 s[34:35], s[12:13]

; __device__ __forceinline__ unsigned v_lane_off(int lane) { return (unsigned)((4 * (lane >> 5) + ((lane & 15) >> 2)) * 64 + ((lane >> 4) & 1) * 32 + (lane & 3) * 8); }
; template <int MODE> ...
;     ...
;     const int r32 = lane & 31, hi = lane >> 5;
;     const int w = __builtin_amdgcn_readfirstlane(tid >> 6);
;     bf16x8 qf[4];
; #pragma unroll
;     for (int d0 = 0; d0 < 4; ++d0) qf[d0] = *(const bf16x8*)(Qrow + r32 * 64 + d0 * 16 + hi * 8);
;     const int kkey = 8 * w + (lane >> 3), kch = (lane & 7) ^ ((kkey >> 1) & 7);
;     const int vkey = 8 * w + ((lane >> 2) & 7), vch = 4 * ((lane >> 5) & 1) + (lane & 3);
;     const bf16_t* kg = Kb + kkey * 64 + kch * 8;
;     const bf16_t* vg = Vb + vkey * 64 + vch * 8;
;     const unsigned ring0 = (unsigned)(unsigned long)ring;
;     const unsigned kdst = (unsigned)__builtin_amdgcn_readfirstlane(ring0 + w * 1024), vdst = kdst + 8192;
;     const float cq = (MODE == 1) ? tab[qpos0 + r32] : 0.f;
;     const float cfar = (MODE == 0) ? tab[256] : 0.f;
;     const unsigned vl = v_lane_off(lane);
;     St S; st_init(S);
.LBB0_603:
	s_mov_b64 s[0:1], -1
	s_cmp_le_u32 s44, s3
	v_lshrrev_b32_e32 v147, 1, v143
	s_cbranch_scc0 .LBB0_631
	v_and_b32_e32 v8, 63, v143
	v_lshrrev_b32_e32 v9, 3, v143
	v_and_b32_e32 v7, 3, v7
	v_and_or_b32 v7, v9, 4, v7
	v_lshlrev_b32_e32 v9, 1, v8
	v_lshlrev_b32_e32 v8, 3, v8
	v_lshlrev_b32_e32 v7, 6, v7
	v_and_b32_e32 v9, 32, v9
	v_and_b32_e32 v8, 24, v8
	s_lshl_b32 s0, s2, 8
	v_lshrrev_b32_e32 v146, 1, v143
	v_readlane_b32 s1, v240, 12
	v_or3_b32 v151, v8, v9, v7
	v_bfe_u32 v7, v143, 1, 3
	v_bitop3_b32 v8, v6, v146, 7 bitop3:0x78
	s_add_i32 s0, s1, s0
	s_lshl_b32 s1, s44, 6
	s_mov_b32 s45, s13
	v_lshl_or_b32 v152, v8, 4, v0
	v_bitop3_b32 v8, v6, v7, 2 bitop3:0x36
	s_sub_i32 s48, s0, s1
	s_lshl_b64 s[0:1], s[44:45], 13
	v_lshl_or_b32 v153, v8, 4, v0
	v_bitop3_b32 v8, v6, v7, 4 bitop3:0x36
	v_bitop3_b32 v7, v6, v7, 6 bitop3:0x36
	v_lshl_add_u64 v[4:5], v[4:5], 0, s[0:1]
	s_mov_b64 s[2:3], 0x4000
	v_lshl_add_u64 v[2:3], v[2:3], 0, s[0:1]
	v_mov_b32_e32 v14, v1
	v_mov_b32_e32 v15, v1
	s_lshr_b32 s41, s40, 1
	v_lshl_or_b32 v154, v8, 4, v0
	v_lshl_or_b32 v155, v7, 4, v0
	v_mad_i32_i24 v156, v6, -4, v144
	v_lshl_add_u64 v[122:123], v[4:5], 0, s[2:3]
	v_lshl_add_u64 v[124:125], v[2:3], 0, s[2:3]
	v_mov_b32_e32 v0, v1
	v_mov_b32_e32 v2, v1
	v_mov_b32_e32 v3, v1
	v_mov_b32_e32 v4, v1
	v_mov_b32_e32 v5, v1
	v_mov_b32_e32 v6, v1
	v_mov_b32_e32 v7, v1
	v_mov_b32_e32 v8, v1
	v_mov_b32_e32 v9, v1
	v_mov_b32_e32 v10, v1
	v_mov_b32_e32 v11, v1
	v_mov_b32_e32 v12, v1
	v_mov_b32_e32 v13, v1
	v_mov_b64_e32 v[30:31], v[14:15]
	v_mov_b64_e32 v[46:47], v[14:15]
	v_sub_u32_e64 v148, s41, 8 clamp
	v_sub_u32_e64 v149, s6, 8 clamp
	s_mov_b32 s0, 0
	v_mov_b32_e32 v157, 0
	s_mov_b32 s49, 0x8000
	s_movk_i32 s45, 0x4000
	v_mov_b32_e32 v150, 0
	v_mov_b64_e32 v[28:29], v[12:13]
	v_mov_b64_e32 v[26:27], v[10:11]
	v_mov_b64_e32 v[24:25], v[8:9]
	v_mov_b64_e32 v[22:23], v[6:7]
	v_mov_b64_e32 v[20:21], v[4:5]
	v_mov_b64_e32 v[18:19], v[2:3]
	v_mov_b64_e32 v[16:17], v[0:1]
	v_mov_b64_e32 v[44:45], v[12:13]
	v_mov_b64_e32 v[42:43], v[10:11]
	v_mov_b64_e32 v[40:41], v[8:9]
	v_mov_b64_e32 v[38:39], v[6:7]
	v_mov_b64_e32 v[36:37], v[4:5]
	v_mov_b64_e32 v[34:35], v[2:3]
	v_mov_b64_e32 v[32:33], v[0:1]
	v_bfe_u32 v239, v143, 5, 1
	v_lshlrev_b32_e32 v239, 2, v239
	v_sub_u32_e32 v239, v239, v144
	v_sub_u32_e32 v238, 0, v144
	v_and_b32_e32 v238, 3, v238
	v_sub_u32_e32 v239, v239, v238
	v_add_u32_e32 v239, 224, v239
	v_lshlrev_b32_e32 v239, 2, v239
	v_mul_u32_u24_e32 v238, 1184, v238
	v_add_u32_e32 v238, v238, v239
	v_add_u32_e32 v238, 137216, v238

; template <int MODE>
; __device__ __forceinline__ void step64(St& S, const bf16x8 (&qf)[4], int t, int qpos0, bool diag, bool first, float cq, float cfar, const LAS float* tab,
;                                        const LAS unsigned char* buf, unsigned vaddr, int r32, int hi) {
;     bf16x8 ka[4], kc[4];
; #pragma unroll
;     for (int d0 = 0; d0 < 4; ++d0) { const int o = r32 * 128 + (((d0 * 2 + hi) ^ ((r32 >> 1) & 7)) << 4); ka[d0] = *(const LAS bf16x8*)(buf + o); kc[d0] = *(const LAS bf16x8*)(buf + 4096 + o); }
;     f32x16 sa, sb;
;     if (MODE == 1) {
;         const float nm = cq - S.m;
; #pragma unroll
;         for (int g = 0; g < 4; ++g) { const f32x4 c0 = *(const LAS f32x4*)(tab + t * 64 + 8 * g + 4 * hi), c1 = *(const LAS f32x4*)(tab + t * 64 + 32 + 8 * g + 4 * hi);
; #pragma unroll
;             for (int e = 0; e < 4; ++e) { sa[4 * g + e] = nm - c0[e]; sb[4 * g + e] = nm - c1[e]; } }
;     } else {
;         if (qpos0 - (t * 64 + 31) >= 128) {
;             const float c = cfar - S.m;
; #pragma unroll
;             for (int r = 0; r < 16; ++r) sa[r] = c;
;         } else {
;             const int dd = qpos0 + r32 - t * 64 + 128;
; #pragma unroll
;             for (int r = 0; r < 16; ++r) { int idx = dd - crow(r, hi); idx = idx < 0 ? 0 : (idx > 256 ? 256 : idx); sa[r] = tab[idx] - S.m; }
;         }
;         if (qpos0 - (t * 64 + 63) >= 128) {
;             const float c = cfar - S.m;
; #pragma unroll
;             for (int r = 0; r < 16; ++r) sb[r] = c;
;         } else {
;             const int dd = qpos0 + r32 - t * 64 - 32 + 128;
; #pragma unroll
;             for (int r = 0; r < 16; ++r) { int idx = dd - crow(r, hi); idx = idx < 0 ? 0 : (idx > 256 ? 256 : idx); sb[r] = tab[idx] - S.m; }
;         }
;     }
; #pragma unroll
;     for (int d0 = 0; d0 < 4; ++d0) { sa = __builtin_amdgcn_mfma_f32_32x32x16_bf16(ka[d0], qf[d0], sa, 0, 0, 0); sb = __builtin_amdgcn_mfma_f32_32x32x16_bf16(kc[d0], qf[d0], sb, 0, 0, 0); }
;     s16x4 vlo[8], vhi[8];
;     ...
;     ATT_TR(vlo[0], 0);           ATT_TR(vhi[0], 1024);          ATT_TR(vlo[1], 2048);        ATT_TR(vhi[1], 3072);
;     ATT_TR(vlo[2], 512);         ATT_TR(vhi[2], 1536);          ATT_TR(vlo[3], 2560);        ATT_TR(vhi[3], 3584);
;     ATT_TR(vlo[4], 4096 + 0);    ATT_TR(vhi[4], 4096 + 1024);   ATT_TR(vlo[5], 4096 + 2048); ATT_TR(vhi[5], 4096 + 3072);
.LBB0_607:
	s_cmp_gt_i32 s44, s41
	v_cmp_lt_i32_e32 vcc, s44, v148
	s_cselect_b64 s[0:1], -1, 0
	s_or_b64 s[0:1], vcc, s[0:1]
	s_and_b64 vcc, exec, s[0:1]
	s_cbranch_vccnz .LBB0_612
	s_add_i32 s2, s50, 0
	s_add_i32 s5, s2, 0x6800
	s_sub_i32 s34, s41, 8
	s_max_i32 s34, s34, 0
	v_add_u32_e32 v0, s2, v152
	v_add_u32_e32 v14, s2, v153
	v_add_u32_e32 v15, s2, v154
	v_add_u32_e32 v234, s2, v155
	ds_read_b128 v[186:189], v0 offset:18432
	ds_read_b128 v[194:197], v14 offset:18432
	ds_read_b128 v[202:205], v15 offset:18432
	ds_read_b128 v[210:213], v234 offset:18432
	ds_read_b128 v[190:193], v0 offset:22528
	ds_read_b128 v[198:201], v14 offset:22528
	ds_read_b128 v[206:209], v15 offset:22528
	ds_read_b128 v[214:217], v234 offset:22528
	v_add_u32_e32 v0, s5, v151
	s_cmp_eq_u32 s44, s34
	s_cbranch_scc0 .Lm0_have_init
	s_add_i32 s35, s48, 63
	s_min_i32 s35, s35, 192
	s_lshl_b32 s35, s35, 2
	v_subrev_u32_e32 v15, s35, v238
	ds_read_b128 v[112:115], v15
	ds_read_b128 v[104:107], v15 offset:32
	ds_read_b128 v[108:111], v15 offset:64
	ds_read_b128 v[100:103], v15 offset:96
	ds_read_b128 v[96:99], v15 offset:128
	ds_read_b128 v[6:9], v15 offset:160
	ds_read_b128 v[10:13], v15 offset:192
	ds_read_b128 v[2:5], v15 offset:224
	s_waitcnt lgkmcnt(0)
	v_sub_f32_e32 v48, v112, v157
	v_sub_f32_e32 v49, v113, v157
	v_sub_f32_e32 v50, v114, v157
	v_sub_f32_e32 v51, v115, v157
	v_sub_f32_e32 v52, v104, v157
	v_sub_f32_e32 v53, v105, v157
	v_sub_f32_e32 v54, v106, v157
	v_sub_f32_e32 v55, v107, v157
	v_sub_f32_e32 v56, v108, v157
	v_sub_f32_e32 v57, v109, v157
	v_sub_f32_e32 v58, v110, v157
	v_sub_f32_e32 v59, v111, v157
	v_sub_f32_e32 v60, v100, v157
	v_sub_f32_e32 v61, v101, v157
	v_sub_f32_e32 v62, v102, v157
	v_sub_f32_e32 v63, v103, v157
	v_sub_f32_e32 v64, v96, v157
	v_sub_f32_e32 v65, v97, v157
	v_sub_f32_e32 v66, v98, v157
	v_sub_f32_e32 v67, v99, v157
	v_sub_f32_e32 v68, v6, v157
	v_sub_f32_e32 v69, v7, v157
	v_sub_f32_e32 v70, v8, v157
	v_sub_f32_e32 v71, v9, v157
	v_sub_f32_e32 v72, v10, v157
	v_sub_f32_e32 v73, v11, v157
	v_sub_f32_e32 v74, v12, v157
	v_sub_f32_e32 v75, v13, v157
	v_sub_f32_e32 v76, v2, v157
	v_sub_f32_e32 v77, v3, v157
	v_sub_f32_e32 v78, v4, v157
	v_sub_f32_e32 v79, v5, v157
	s_nop 1
.Lm0_have_init:
	s_waitcnt lgkmcnt(7)
	v_mfma_f32_32x32x16_bf16 v[48:63], v[186:189], v[80:83], v[48:63]
	s_waitcnt lgkmcnt(6)
	v_mfma_f32_32x32x16_bf16 v[48:63], v[194:197], v[84:87], v[48:63]
	s_waitcnt lgkmcnt(5)
	v_mfma_f32_32x32x16_bf16 v[48:63], v[202:205], v[88:91], v[48:63]
	s_waitcnt lgkmcnt(4)
	v_mfma_f32_32x32x16_bf16 v[48:63], v[210:213], v[92:95], v[48:63]
	s_waitcnt lgkmcnt(3)
	v_mfma_f32_32x32x16_bf16 v[64:79], v[190:193], v[80:83], v[64:79]
	ds_read_b64_tr_b16 v[112:113], v0
	ds_read_b64_tr_b16 v[114:115], v0 offset:1024
	ds_read_b64_tr_b16 v[104:105], v0 offset:2048
	ds_read_b64_tr_b16 v[106:107], v0 offset:3072
	s_waitcnt lgkmcnt(6)
	v_mfma_f32_32x32x16_bf16 v[64:79], v[198:201], v[84:87], v[64:79]
	ds_read_b64_tr_b16 v[108:109], v0 offset:512
	ds_read_b64_tr_b16 v[110:111], v0 offset:1536
	ds_read_b64_tr_b16 v[100:101], v0 offset:2560
	ds_read_b64_tr_b16 v[102:103], v0 offset:3584
	s_waitcnt lgkmcnt(9)
	v_mfma_f32_32x32x16_bf16 v[64:79], v[206:209], v[88:91], v[64:79]
	ds_read_b64_tr_b16 v[96:97], v0 offset:4096
	ds_read_b64_tr_b16 v[98:99], v0 offset:5120
	ds_read_b64_tr_b16 v[6:7], v0 offset:6144
	ds_read_b64_tr_b16 v[8:9], v0 offset:7168
	s_waitcnt lgkmcnt(12)
	v_mfma_f32_32x32x16_bf16 v[64:79], v[214:217], v[92:95], v[64:79]
	s_waitcnt lgkmcnt(11)
	ds_read_b64_tr_b16 v[10:11], v0 offset:4608
	ds_read_b64_tr_b16 v[12:13], v0 offset:5632
	ds_read_b64_tr_b16 v[2:3], v0 offset:6656
	ds_read_b64_tr_b16 v[4:5], v0 offset:7680
	s_nop 1
	v_max3_f32 v0, v48, v49, v50
	v_max3_f32 v0, v0, v51, v52
	v_max3_f32 v0, v0, v53, v54
	v_max3_f32 v0, v0, v55, v56
	v_max3_f32 v0, v0, v57, v58
	v_max3_f32 v0, v0, v59, v60
	v_max3_f32 v0, v0, v61, v62
	s_nop 1
	v_max3_f32 v14, v64, v65, v66
	v_max3_f32 v14, v14, v67, v68
	v_max3_f32 v14, v14, v69, v70
	v_max3_f32 v14, v14, v71, v72
	v_max3_f32 v14, v14, v73, v74
	v_max3_f32 v14, v14, v75, v76
	v_max3_f32 v14, v14, v77, v78
	v_max_f32_e32 v15, v63, v79
	v_max3_f32 v0, v0, v14, v15
	s_nop 0
	v_mov_b32_e32 v14, v0
	s_nop 1
	v_permlane32_swap_b32_e32 v0, v14
	v_max_f32_e32 v14, v0, v14
	s_cmp_eq_u32 s44, s34
	s_cbranch_scc1 .Lm0_first
	s_mov_b32 s5, 0x41000000
	v_cmp_lt_f32_e32 vcc, s5, v14
	s_nop 3
	s_cbranch_vccz .Lm0_norescale
	v_max_f32_e32 v0, 0, v14
	v_exp_f32_e64 v14, -v0
	v_add_f32_e32 v157, v157, v0
	v_sub_f32_e32 v48, v48, v0
	v_sub_f32_e32 v49, v49, v0
	v_sub_f32_e32 v50, v50, v0
	v_sub_f32_e32 v51, v51, v0
	v_sub_f32_e32 v52, v52, v0
	v_sub_f32_e32 v53, v53, v0
	v_sub_f32_e32 v54, v54, v0
	v_sub_f32_e32 v55, v55, v0
	v_sub_f32_e32 v56, v56, v0
	v_sub_f32_e32 v57, v57, v0
	v_sub_f32_e32 v58, v58, v0
	v_sub_f32_e32 v59, v59, v0
	v_sub_f32_e32 v60, v60, v0
	v_sub_f32_e32 v61, v61, v0
	v_sub_f32_e32 v62, v62, v0
	v_sub_f32_e32 v63, v63, v0
	v_sub_f32_e32 v64, v64, v0
	v_sub_f32_e32 v65, v65, v0
	v_sub_f32_e32 v66, v66, v0
	v_sub_f32_e32 v67, v67, v0
	v_sub_f32_e32 v68, v68, v0
	v_sub_f32_e32 v69, v69, v0
	v_sub_f32_e32 v70, v70, v0
	v_sub_f32_e32 v71, v71, v0
	v_sub_f32_e32 v72, v72, v0
	v_sub_f32_e32 v73, v73, v0
	v_sub_f32_e32 v74, v74, v0
	v_sub_f32_e32 v75, v75, v0
	v_sub_f32_e32 v76, v76, v0
	v_sub_f32_e32 v77, v77, v0
	v_sub_f32_e32 v78, v78, v0
	v_sub_f32_e32 v79, v79, v0
	v_mul_f32_e32 v150, v150, v14
	v_mul_f32_e32 v16, v16, v14
	v_mul_f32_e32 v17, v17, v14
	v_mul_f32_e32 v18, v18, v14
	v_mul_f32_e32 v19, v19, v14
	v_mul_f32_e32 v20, v20, v14
	v_mul_f32_e32 v21, v21, v14
	v_mul_f32_e32 v22, v22, v14
	v_mul_f32_e32 v23, v23, v14
	v_mul_f32_e32 v24, v24, v14
	v_mul_f32_e32 v25, v25, v14
	v_mul_f32_e32 v26, v26, v14
	v_mul_f32_e32 v27, v27, v14
	v_mul_f32_e32 v28, v28, v14
	v_mul_f32_e32 v29, v29, v14
	v_mul_f32_e32 v30, v30, v14
	v_mul_f32_e32 v31, v31, v14
	v_mul_f32_e32 v32, v32, v14
	v_mul_f32_e32 v33, v33, v14
	v_mul_f32_e32 v34, v34, v14
	v_mul_f32_e32 v35, v35, v14
	v_mul_f32_e32 v36, v36, v14
	v_mul_f32_e32 v37, v37, v14
	v_mul_f32_e32 v38, v38, v14
	v_mul_f32_e32 v39, v39, v14
	v_mul_f32_e32 v40, v40, v14
	v_mul_f32_e32 v41, v41, v14
	v_mul_f32_e32 v42, v42, v14
	v_mul_f32_e32 v43, v43, v14
	v_mul_f32_e32 v44, v44, v14
	v_mul_f32_e32 v45, v45, v14
	v_mul_f32_e32 v46, v46, v14
	v_mul_f32_e32 v47, v47, v14
	s_branch .Lm0_norescale
; template <int MODE>
; __device__ __forceinline__ void step64(St& S, const bf16x8 (&qf)[4], int t, int qpos0, bool diag, bool first, float cq, float cfar, const LAS float* tab,
;                                        const LAS unsigned char* buf, unsigned vaddr, int r32, int hi) {
;     ...
;             const int dd = qpos0 + r32 - t * 64 + 128;
; #pragma unroll
;     ...
;     if (first || __any(rm > THR)) {
;         const float dl = first ? rm : fmaxf(rm, 0.f); S.m += dl;
;         const float f = first ? 1.0f : __builtin_amdgcn_exp2f(-dl); S.l *= f;
; #pragma unroll
;         for (int r = 0; r < 16; ++r) { sa[r] -= dl; sb[r] -= dl; S.o0[r] *= f; S.o1[r] *= f; }
;     }
; #pragma unroll
;     for (int r = 0; r < 16; ++r) { sa[r] = __builtin_amdgcn_exp2f(sa[r]); sb[r] = __builtin_amdgcn_exp2f(sb[r]); }
;     asm volatile("s_waitcnt lgkmcnt(0)" ::: "memory");
;     __builtin_amdgcn_sched_barrier(0);
;     u32x4 pa0, pa1, pb0, pb1;
;     pa0.x = pk2(sa[0], sa[1]); pa0.y = pk2(sa[2], sa[3]); pa0.z = pk2(sa[4], sa[5]); pa0.w = pk2(sa[6], sa[7]);
;     pa1.x = pk2(sa[8], sa[9]); pa1.y = pk2(sa[10], sa[11]); pa1.z = pk2(sa[12], sa[13]); pa1.w = pk2(sa[14], sa[15]);
;     pb0.x = pk2(sb[0], sb[1]); pb0.y = pk2(sb[2], sb[3]); pb0.z = pk2(sb[4], sb[5]); pb0.w = pk2(sb[6], sb[7]);
;     pb1.x = pk2(sb[8], sb[9]); pb1.y = pk2(sb[10], sb[11]); pb1.z = pk2(sb[12], sb[13]); pb1.w = pk2(sb[14], sb[15]);
;     ...
;     S.o0 = __builtin_amdgcn_mfma_f32_32x32x16_bf16(ATT_VF(0), ATT_PF(pa0), S.o0, 0, 0, 0);
;     S.o1 = __builtin_amdgcn_mfma_f32_32x32x16_bf16(ATT_VF(2), ATT_PF(pa0), S.o1, 0, 0, 0);
;     S.o0 = __builtin_amdgcn_mfma_f32_32x32x16_bf16(ATT_VF(1), ATT_PF(pa1), S.o0, 0, 0, 0);
;     S.o1 = __builtin_amdgcn_mfma_f32_32x32x16_bf16(ATT_VF(3), ATT_PF(pa1), S.o1, 0, 0, 0);
;     S.o0 = __builtin_amdgcn_mfma_f32_32x32x16_bf16(ATT_VF(4), ATT_PF(pb0), S.o0, 0, 0, 0);
;     S.o1 = __builtin_amdgcn_mfma_f32_32x32x16_bf16(ATT_VF(6), ATT_PF(pb0), S.o1, 0, 0, 0);
;     S.o0 = __builtin_amdgcn_mfma_f32_32x32x16_bf16(ATT_VF(5), ATT_PF(pb1), S.o0, 0, 0, 0);
;     S.o1 = __builtin_amdgcn_mfma_f32_32x32x16_bf16(ATT_VF(7), ATT_PF(pb1), S.o1, 0, 0, 0);
;     ...
;     float l0 = 0.f, l1 = 0.f, l2 = 0.f, l3 = 0.f;
; #pragma unroll
;     for (int r = 0; r < 16; r += 2) { l0 += sa[r]; l1 += sa[r + 1]; l2 += sb[r]; l3 += sb[r + 1]; }
;     S.l += (l0 + l1) + (l2 + l3);
.Lm0_first:
	v_add_f32_e32 v157, v157, v14
	v_sub_f32_e32 v48, v48, v14
	v_sub_f32_e32 v49, v49, v14
	v_sub_f32_e32 v50, v50, v14
	v_sub_f32_e32 v51, v51, v14
	v_sub_f32_e32 v52, v52, v14
	v_sub_f32_e32 v53, v53, v14
	v_sub_f32_e32 v54, v54, v14
	v_sub_f32_e32 v55, v55, v14
	v_sub_f32_e32 v56, v56, v14
	v_sub_f32_e32 v57, v57, v14
	v_sub_f32_e32 v58, v58, v14
	v_sub_f32_e32 v59, v59, v14
	v_sub_f32_e32 v60, v60, v14
	v_sub_f32_e32 v61, v61, v14
	v_sub_f32_e32 v62, v62, v14
	v_sub_f32_e32 v63, v63, v14
	v_sub_f32_e32 v64, v64, v14
	v_sub_f32_e32 v65, v65, v14
	v_sub_f32_e32 v66, v66, v14
	v_sub_f32_e32 v67, v67, v14
	v_sub_f32_e32 v68, v68, v14
	v_sub_f32_e32 v69, v69, v14
	v_sub_f32_e32 v70, v70, v14
	v_sub_f32_e32 v71, v71, v14
	v_sub_f32_e32 v72, v72, v14
	v_sub_f32_e32 v73, v73, v14
	v_sub_f32_e32 v74, v74, v14
	v_sub_f32_e32 v75, v75, v14
	v_sub_f32_e32 v76, v76, v14
	v_sub_f32_e32 v77, v77, v14
	v_sub_f32_e32 v78, v78, v14
	v_sub_f32_e32 v79, v79, v14
.Lm0_norescale:
	s_waitcnt lgkmcnt(0)
	s_cmp_ge_i32 s44, s41
	s_cbranch_scc1 .Lm0_pv
	s_add_i32 s35, s48, -1
	s_min_i32 s35, s35, 192
	s_lshl_b32 s35, s35, 2
	v_subrev_u32_e32 v15, s35, v238
	ds_read_b128 v[186:189], v15
	ds_read_b128 v[190:193], v15 offset:32
	ds_read_b128 v[194:197], v15 offset:64
	ds_read_b128 v[198:201], v15 offset:96
	ds_read_b128 v[202:205], v15 offset:128
	ds_read_b128 v[206:209], v15 offset:160
	ds_read_b128 v[210:213], v15 offset:192
	ds_read_b128 v[214:217], v15 offset:224
.Lm0_pv:
	v_exp_f32_e32 v48, v48
	v_exp_f32_e32 v49, v49
	v_exp_f32_e32 v50, v50
	v_exp_f32_e32 v51, v51
	v_exp_f32_e32 v52, v52
	v_exp_f32_e32 v53, v53
	v_exp_f32_e32 v54, v54
	v_exp_f32_e32 v55, v55
	v_cvt_pk_bf16_f32 v218, v48, v49
	v_cvt_pk_bf16_f32 v219, v50, v51
	v_cvt_pk_bf16_f32 v220, v52, v53
	v_cvt_pk_bf16_f32 v221, v54, v55
	v_exp_f32_e32 v56, v56
	v_exp_f32_e32 v57, v57
	v_mfma_f32_32x32x16_bf16 v[32:47], v[112:115], v[218:221], v[32:47]
	v_exp_f32_e32 v58, v58
	v_exp_f32_e32 v59, v59
	v_exp_f32_e32 v60, v60
	v_exp_f32_e32 v61, v61
	v_exp_f32_e32 v62, v62
	v_exp_f32_e32 v63, v63
	v_mfma_f32_32x32x16_bf16 v[16:31], v[108:111], v[218:221], v[16:31]
	v_cvt_pk_bf16_f32 v222, v56, v57
	v_cvt_pk_bf16_f32 v223, v58, v59
	v_cvt_pk_bf16_f32 v224, v60, v61
	v_cvt_pk_bf16_f32 v225, v62, v63
	v_add_f32_e32 v0, v48, v50
	v_add_f32_e32 v0, v0, v52
	v_add_f32_e32 v14, v49, v51
	v_add_f32_e32 v14, v14, v53
	v_mfma_f32_32x32x16_bf16 v[32:47], v[104:107], v[222:225], v[32:47]
	v_exp_f32_e32 v64, v64
	v_exp_f32_e32 v65, v65
	v_exp_f32_e32 v66, v66
	v_exp_f32_e32 v67, v67
	v_exp_f32_e32 v68, v68
	v_exp_f32_e32 v69, v69
	v_exp_f32_e32 v70, v70
	v_exp_f32_e32 v71, v71
	v_mfma_f32_32x32x16_bf16 v[16:31], v[100:103], v[222:225], v[16:31]
	v_cvt_pk_bf16_f32 v226, v64, v65
	v_cvt_pk_bf16_f32 v227, v66, v67
	v_cvt_pk_bf16_f32 v228, v68, v69
	v_cvt_pk_bf16_f32 v229, v70, v71
	v_add_f32_e32 v0, v0, v54
	v_add_f32_e32 v0, v0, v56
	v_add_f32_e32 v14, v14, v55
	v_add_f32_e32 v14, v14, v57
	v_mfma_f32_32x32x16_bf16 v[32:47], v[96:99], v[226:229], v[32:47]
	v_exp_f32_e32 v72, v72
	v_exp_f32_e32 v73, v73
	v_exp_f32_e32 v74, v74
	v_exp_f32_e32 v75, v75
	v_exp_f32_e32 v76, v76
	v_exp_f32_e32 v77, v77
	v_exp_f32_e32 v78, v78
	v_exp_f32_e32 v79, v79
	v_mfma_f32_32x32x16_bf16 v[16:31], v[10:13], v[226:229], v[16:31]
	v_cvt_pk_bf16_f32 v230, v72, v73
	v_cvt_pk_bf16_f32 v231, v74, v75
	v_cvt_pk_bf16_f32 v232, v76, v77
	v_cvt_pk_bf16_f32 v233, v78, v79
	v_add_f32_e32 v0, v0, v58
	v_add_f32_e32 v0, v0, v60
	v_add_f32_e32 v0, v0, v62
	v_add_f32_e32 v14, v14, v59
	v_add_f32_e32 v14, v14, v61
	v_add_f32_e32 v14, v14, v63
	v_mfma_f32_32x32x16_bf16 v[32:47], v[6:9], v[230:233], v[32:47]
	v_add_f32_e32 v15, v64, v66
	v_add_f32_e32 v15, v15, v68
	v_add_f32_e32 v15, v15, v70
	v_add_f32_e32 v15, v15, v72
	v_add_f32_e32 v234, v65, v67
	v_add_f32_e32 v234, v234, v69
	v_add_f32_e32 v234, v234, v71
	v_add_f32_e32 v234, v234, v73
	v_mfma_f32_32x32x16_bf16 v[16:31], v[2:5], v[230:233], v[16:31]
	v_add_f32_e32 v15, v15, v74
	v_add_f32_e32 v15, v15, v76
	v_add_f32_e32 v15, v15, v78
	v_add_f32_e32 v234, v234, v75
	v_add_f32_e32 v234, v234, v77
	v_add_f32_e32 v234, v234, v79
	v_add_f32_e32 v0, v0, v14
	v_add_f32_e32 v15, v15, v234
	v_add_f32_e32 v0, v0, v15
	v_add_f32_e32 v150, v150, v0
	s_cmp_ge_i32 s44, s41
	s_cbranch_scc1 .Lm0_end
	s_waitcnt lgkmcnt(0)
	v_sub_f32_e32 v48, v186, v157
	v_sub_f32_e32 v49, v187, v157
	v_sub_f32_e32 v50, v188, v157
	v_sub_f32_e32 v51, v189, v157
	v_sub_f32_e32 v52, v190, v157
	v_sub_f32_e32 v53, v191, v157
	v_sub_f32_e32 v54, v192, v157
	v_sub_f32_e32 v55, v193, v157
	v_sub_f32_e32 v56, v194, v157
	v_sub_f32_e32 v57, v195, v157
	v_sub_f32_e32 v58, v196, v157
	v_sub_f32_e32 v59, v197, v157
	v_sub_f32_e32 v60, v198, v157
	v_sub_f32_e32 v61, v199, v157
	v_sub_f32_e32 v62, v200, v157
	v_sub_f32_e32 v63, v201, v157
	v_sub_f32_e32 v64, v202, v157
	v_sub_f32_e32 v65, v203, v157
	v_sub_f32_e32 v66, v204, v157
	v_sub_f32_e32 v67, v205, v157
	v_sub_f32_e32 v68, v206, v157
	v_sub_f32_e32 v69, v207, v157
	v_sub_f32_e32 v70, v208, v157
	v_sub_f32_e32 v71, v209, v157
	v_sub_f32_e32 v72, v210, v157
	v_sub_f32_e32 v73, v211, v157
	v_sub_f32_e32 v74, v212, v157
	v_sub_f32_e32 v75, v213, v157
	v_sub_f32_e32 v76, v214, v157
	v_sub_f32_e32 v77, v215, v157
	v_sub_f32_e32 v78, v216, v157
	v_sub_f32_e32 v79, v217, v157
.Lm0_end:
	s_mov_b64 s[0:1], -1
	s_and_b64 vcc, exec, s[46:47]
	s_cbranch_vccnz .LBB0_613
	s_branch .LBB0_626

; __device__ __forceinline__ int crow(int r, int hi) { return (r & 3) + 8 * (r >> 2) + 4 * hi; }
; template <int MODE>
; __device__ __forceinline__ void step64(St& S, const bf16x8 (&qf)[4], int t, int qpos0, bool diag, bool first, float cq, float cfar, const LAS float* tab,
;                                        const LAS unsigned char* buf, unsigned vaddr, int r32, int hi) {
;     ...
;         if (qpos0 - (t * 64 + 31) >= 128) {
;             const float c = cfar - S.m;
; #pragma unroll
;             for (int r = 0; r < 16; ++r) sa[r] = c;
;         } else {
;             const int dd = qpos0 + r32 - t * 64 + 128;
; #pragma unroll
;             for (int r = 0; r < 16; ++r) { int idx = dd - crow(r, hi); idx = idx < 0 ? 0 : (idx > 256 ? 256 : idx); sa[r] = tab[idx] - S.m; }
; template <int MODE> ...
;     ...
;         if (more) asm volatile("s_waitcnt vmcnt(2) lgkmcnt(0)\n\ts_barrier" ::: "memory");
;         else      asm volatile("s_waitcnt vmcnt(0) lgkmcnt(0)\n\ts_barrier" ::: "memory");
.LBB0_613:
	s_waitcnt vmcnt(0) lgkmcnt(0)
	s_barrier
	s_branch .LBB0_628

; #define LAS __attribute__((address_space(3)))
; template <int MODE> ...
;     ...
;     for (int s = T0; s < T1; ++s) {
;         const int t = SU_T(s);
;         const bool more = (s + 2 < T1);
;         if (more) { glds16(kg + (size_t)SU_T(s + 2) * 4096, kdst + s2); glds16(vg + (size_t)SU_T(s + 2) * 4096, vdst + s2); }
;         LAS unsigned char* buf = ring + s0;
;         if (t >= t_lo && t < t_hi)
;             step64<MODE>(S, qf, t, qpos0, t == t_hi - 1, REV ? (t == t_hi - 1) : (t == t_lo), cq, cfar, tab, buf, (unsigned)(unsigned long)(buf + 8192) + vl, r32, hi);
;         if (more) asm volatile("s_waitcnt vmcnt(2) lgkmcnt(0)\n\ts_barrier" ::: "memory");
;         else      asm volatile("s_waitcnt vmcnt(0) lgkmcnt(0)\n\ts_barrier" ::: "memory");
;         const int sn = s0; s0 = s1; s1 = s2; s2 = sn;
;     }
.LBB0_628:
	s_add_i32 s44, s44, 1
	s_sub_i32 s48, s48, 64
	v_lshl_add_u64 v[122:123], v[122:123], 0, s[66:67]
	s_cmp_ge_u32 s44, s15
	v_lshl_add_u64 v[124:125], v[124:125], 0, s[66:67]
	s_cbranch_scc1 .LBB0_656
	s_mov_b32 s0, s45
	s_mov_b32 s45, s49
	s_mov_b32 s49, s50
	s_branch .LBB0_605
.LBB0_631:
	s_and_b64 vcc, exec, s[0:1]
	s_cbranch_vccz .LBB0_633
	v_mov_b32_e32 v14, v1
	v_mov_b32_e32 v15, v1
	v_mov_b32_e32 v0, v1
	v_mov_b32_e32 v2, v1
	v_mov_b32_e32 v3, v1
	v_mov_b32_e32 v4, v1
	v_mov_b32_e32 v5, v1
	v_mov_b32_e32 v6, v1
	v_mov_b32_e32 v7, v1
	v_mov_b32_e32 v8, v1
	v_mov_b32_e32 v9, v1
	v_mov_b32_e32 v10, v1
	v_mov_b32_e32 v11, v1
	v_mov_b32_e32 v12, v1
	v_mov_b32_e32 v13, v1
	v_mov_b64_e32 v[46:47], v[14:15]
	v_mov_b64_e32 v[30:31], v[14:15]
	v_mov_b32_e32 v150, 0
	v_mov_b32_e32 v146, v147
	v_mov_b64_e32 v[44:45], v[12:13]
	v_mov_b64_e32 v[42:43], v[10:11]
	v_mov_b64_e32 v[40:41], v[8:9]
	v_mov_b64_e32 v[38:39], v[6:7]
	v_mov_b64_e32 v[36:37], v[4:5]
	v_mov_b64_e32 v[34:35], v[2:3]
	v_mov_b64_e32 v[32:33], v[0:1]
	v_mov_b64_e32 v[28:29], v[12:13]
	v_mov_b64_e32 v[26:27], v[10:11]
	v_mov_b64_e32 v[24:25], v[8:9]
	v_mov_b64_e32 v[22:23], v[6:7]
	v_mov_b64_e32 v[20:21], v[4:5]
	v_mov_b64_e32 v[18:19], v[2:3]
	v_mov_b64_e32 v[16:17], v[0:1]
